# dilated attention: lean next-unit prefetch (scalar base + 32-bit offsets, 5 VALU per row load) when all rows in range; original path kept for the first query block
# speedup vs baseline: 1.0118x; 1.0018x over previous
.LBB0_716:
	s_add_i32 s77, s4, s83
	s_cmp_ge_i32 s77, s70
	s_cselect_b64 s[30:31], -1, 0
	s_and_b64 vcc, exec, s[30:31]
	s_waitcnt vmcnt(0)
	ds_write_b128 v199, v[68:71]
	ds_write_b128 v200, v[64:67]
	ds_write_b128 v201, v[72:75]
	ds_write_b128 v202, v[76:79]
	ds_write_b128 v203, v[80:83]
	ds_write_b128 v204, v[84:87]
	ds_write_b128 v205, v[88:91]
	ds_write_b128 v206, v[92:95]
	ds_write_b128 v207, v[96:99]
	ds_write_b128 v208, v[100:103]
	ds_write_b128 v209, v[104:107]
	ds_write_b128 v210, v[108:111]
	ds_write_b128 v211, v[112:115]
	ds_write_b128 v212, v[116:119]
	ds_write_b128 v213, v[120:123]
	ds_write_b128 v214, v[124:127]
	s_waitcnt lgkmcnt(0)
	s_barrier
	s_cbranch_vccnz .LBB0_750
	s_abs_i32 s1, s77
	s_mul_hi_u32 s2, s1, s72
	s_mul_i32 s3, s2, s41
	s_sub_i32 s1, s1, s3
	s_ashr_i32 s0, s77, 31
	s_add_i32 s3, s2, 1
	s_sub_i32 s5, s1, s41
	s_cmp_ge_u32 s1, s41
	s_cselect_b32 s2, s3, s2
	s_cselect_b32 s1, s5, s1
	s_add_i32 s3, s2, 1
	s_cmp_ge_u32 s1, s41
	s_cselect_b32 s1, s3, s2
	s_xor_b32 s1, s1, s0
	s_sub_i32 s1, s1, s0
	s_ashr_i32 s0, s1, 31
	s_lshr_b32 s0, s0, 28
	s_add_i32 s0, s1, s0
	s_ashr_i32 s2, s0, 4
	s_abs_i32 s5, s2
	s_mul_hi_u32 s6, s5, s73
	s_mul_i32 s7, s6, s40
	s_and_b32 s3, s0, 0x3fffff0
	s_sub_i32 s5, s5, s7
	s_sub_i32 s3, s1, s3
	s_ashr_i32 s0, s0, 31
	s_add_i32 s7, s6, 1
	s_sub_i32 s8, s5, s40
	s_cmp_ge_u32 s5, s40
	s_cselect_b32 s6, s7, s6
	s_cselect_b32 s5, s8, s5
	s_add_i32 s7, s6, 1
	s_cmp_ge_u32 s5, s40
	s_cselect_b32 s5, s7, s6
	s_xor_b32 s5, s5, s0
	s_mul_i32 s1, s74, s1
	s_add_i32 s6, s76, s75
	s_sub_i32 s0, s5, s0
	s_add_i32 s6, s6, s1
	s_mul_i32 s5, s0, s40
	s_add_i32 s7, s6, 0xffffff80
	s_sub_i32 s2, s2, s5
	s_ashr_i32 s1, s0, 31
	v_mov_b32_e32 v1, s6
	v_mov_b32_e32 v2, s7
	s_lshl_b64 s[0:1], s[0:1], 13
	s_ashr_i32 s5, s2, 31
	v_cndmask_b32_e64 v1, v1, v2, s[36:37]
	v_mov_b32_e32 v66, v0
	v_mov_b32_e32 v67, v0
	s_add_u32 s0, s0, s2
	v_add_u32_e32 v2, v149, v1
	v_mov_b32_e32 v64, v0
	v_mov_b32_e32 v65, v0
	v_mov_b64_e32 v[70:71], v[66:67]
	s_addc_u32 s1, s1, s5
	s_lshl_b32 s5, s3, 6
	v_cmp_lt_i32_e32 vcc, -1, v2
	v_mov_b64_e32 v[68:69], v[64:65]
	s_cmp_lt_i32 s7, 0
	s_cbranch_scc1 .Ldil_pf_slow
	v_readlane_b32 s8, v254, 27
	v_readlane_b32 s9, v254, 28
	s_mul_i32 s2, s0, 0x1800
	s_mul_hi_u32 s3, s0, 0x1800
	s_mul_i32 s1, s1, 0x1800
	v_mov_b32_e32 v1, s6
	v_mov_b32_e32 v2, s7
	s_add_i32 s3, s3, s1
	s_add_u32 s8, s8, s2
	s_addc_u32 s9, s9, s3
	s_lshl_b32 s2, s5, 1
	s_add_u32 s8, s8, s2
	s_addc_u32 s9, s9, 0
	v_cndmask_b32_e64 v3, v1, v2, s[36:37]
	v_add_u32_e32 v3, v149, v3
	v_lshlrev_b32_e32 v3, s71, v3
	v_mul_u32_u24_e32 v3, 0x1800, v3
	v_lshl_add_u32 v3, v150, 1, v3
	global_load_dwordx4 v[68:71], v3, s[8:9]
	v_cndmask_b32_e64 v4, v1, v2, s[38:39]
	v_add_u32_e32 v4, v151, v4
	v_lshlrev_b32_e32 v4, s71, v4
	v_mul_u32_u24_e32 v4, 0x1800, v4
	v_lshl_add_u32 v4, v152, 1, v4
	global_load_dwordx4 v[64:67], v4, s[8:9]
	v_cndmask_b32_e64 v5, v1, v2, s[20:21]
	v_add_u32_e32 v5, v153, v5
	v_lshlrev_b32_e32 v5, s71, v5
	v_mul_u32_u24_e32 v5, 0x1800, v5
	v_lshl_add_u32 v5, v154, 1, v5
	global_load_dwordx4 v[72:75], v5, s[8:9]
	v_cndmask_b32_e64 v6, v1, v2, s[42:43]
	v_add_u32_e32 v6, v155, v6
	v_lshlrev_b32_e32 v6, s71, v6
	v_mul_u32_u24_e32 v6, 0x1800, v6
	v_lshl_add_u32 v6, v156, 1, v6
	global_load_dwordx4 v[76:79], v6, s[8:9]
	v_cndmask_b32_e64 v3, v1, v2, s[44:45]
	v_add_u32_e32 v3, v157, v3
	v_lshlrev_b32_e32 v3, s71, v3
	v_mul_u32_u24_e32 v3, 0x1800, v3
	v_lshl_add_u32 v3, v158, 1, v3
	global_load_dwordx4 v[80:83], v3, s[8:9]
	v_cndmask_b32_e64 v4, v1, v2, s[46:47]
	v_add_u32_e32 v4, v159, v4
	v_lshlrev_b32_e32 v4, s71, v4
	v_mul_u32_u24_e32 v4, 0x1800, v4
	v_lshl_add_u32 v4, v160, 1, v4
	global_load_dwordx4 v[84:87], v4, s[8:9]
	v_cndmask_b32_e64 v5, v1, v2, s[48:49]
	v_add_u32_e32 v5, v161, v5
	v_lshlrev_b32_e32 v5, s71, v5
	v_mul_u32_u24_e32 v5, 0x1800, v5
	v_lshl_add_u32 v5, v171, 1, v5
	global_load_dwordx4 v[88:91], v5, s[8:9]
	v_cndmask_b32_e64 v6, v1, v2, s[50:51]
	v_add_u32_e32 v6, v172, v6
	v_lshlrev_b32_e32 v6, s71, v6
	v_mul_u32_u24_e32 v6, 0x1800, v6
	v_lshl_add_u32 v6, v173, 1, v6
	global_load_dwordx4 v[92:95], v6, s[8:9]
	v_cndmask_b32_e64 v3, v1, v2, s[52:53]
	v_add_u32_e32 v3, v174, v3
	v_lshlrev_b32_e32 v3, s71, v3
	v_mul_u32_u24_e32 v3, 0x1800, v3
	v_lshl_add_u32 v3, v175, 1, v3
	global_load_dwordx4 v[96:99], v3, s[8:9]
	v_cndmask_b32_e64 v4, v1, v2, s[54:55]
	v_add_u32_e32 v4, v176, v4
	v_lshlrev_b32_e32 v4, s71, v4
	v_mul_u32_u24_e32 v4, 0x1800, v4
	v_lshl_add_u32 v4, v177, 1, v4
	global_load_dwordx4 v[100:103], v4, s[8:9]
	v_cndmask_b32_e64 v5, v1, v2, s[56:57]
	v_add_u32_e32 v5, v178, v5
	v_lshlrev_b32_e32 v5, s71, v5
	v_mul_u32_u24_e32 v5, 0x1800, v5
	v_lshl_add_u32 v5, v179, 1, v5
	global_load_dwordx4 v[104:107], v5, s[8:9]
	v_cndmask_b32_e64 v6, v1, v2, s[58:59]
	v_add_u32_e32 v6, v180, v6
	v_lshlrev_b32_e32 v6, s71, v6
	v_mul_u32_u24_e32 v6, 0x1800, v6
	v_lshl_add_u32 v6, v181, 1, v6
	global_load_dwordx4 v[108:111], v6, s[8:9]
	v_cndmask_b32_e64 v3, v1, v2, s[60:61]
	v_add_u32_e32 v3, v182, v3
	v_lshlrev_b32_e32 v3, s71, v3
	v_mul_u32_u24_e32 v3, 0x1800, v3
	v_lshl_add_u32 v3, v183, 1, v3
	global_load_dwordx4 v[112:115], v3, s[8:9]
	v_cndmask_b32_e64 v4, v1, v2, s[62:63]
	v_add_u32_e32 v4, v184, v4
	v_lshlrev_b32_e32 v4, s71, v4
	v_mul_u32_u24_e32 v4, 0x1800, v4
	v_lshl_add_u32 v4, v185, 1, v4
	global_load_dwordx4 v[116:119], v4, s[8:9]
	v_cndmask_b32_e64 v5, v1, v2, s[64:65]
	v_add_u32_e32 v5, v186, v5
	v_lshlrev_b32_e32 v5, s71, v5
	v_mul_u32_u24_e32 v5, 0x1800, v5
	v_lshl_add_u32 v5, v187, 1, v5
	global_load_dwordx4 v[120:123], v5, s[8:9]
	v_cndmask_b32_e64 v6, v1, v2, s[66:67]
	v_add_u32_e32 v6, v188, v6
	v_lshlrev_b32_e32 v6, s71, v6
	v_mul_u32_u24_e32 v6, 0x1800, v6
	v_lshl_add_u32 v6, v189, 1, v6
	global_load_dwordx4 v[124:127], v6, s[8:9]
	s_branch .LBB0_750
.Ldil_pf_slow:
	s_and_saveexec_b64 s[2:3], vcc
	s_cbranch_execz .LBB0_719
	v_mov_b32_e32 v3, v0
	v_readlane_b32 s8, v254, 27
	v_lshlrev_b64 v[2:3], s71, v[2:3]
	v_readlane_b32 s9, v254, 28
	v_lshl_add_u64 v[2:3], v[2:3], 0, s[0:1]
	v_add_u32_e32 v4, s5, v150
	v_mov_b64_e32 v[6:7], s[8:9]
	v_mad_u64_u32 v[6:7], s[8:9], v2, s82, v[6:7]
	v_mad_i32_i24 v7, v3, s82, v7
	v_ashrrev_i32_e32 v5, 31, v4
	v_lshl_add_u64 v[2:3], v[4:5], 1, v[6:7]
	global_load_dwordx4 v[68:71], v[2:3], off
